# panel-group conv fix-up: second call's items dealt to the group's second workgroup (2 dependent round trips per WG instead of 4 on one), on top of the de-serialised P2 prologue
# baseline (speedup 1.0000x reference)
; __device__ __forceinline__ void conv_fixup(Frame& F, const Ptrs& P, int first, int count, int gw, int NGW) {
;     const bf16* U = (const bf16*)(P.ws + WS_U); const bf16* GB = (const bf16*)(P.ws + WS_GB); bf16* BR = (bf16*)(P.ws + WS_BR);
;     const int ch0 = F.lane * 8;
;     const f32x4 w0a = *(const f32x4*)(P.conv_w + ch0), w0b = *(const f32x4*)(P.conv_w + ch0 + 4);
;     const f32x4 w1a = *(const f32x4*)(P.conv_w + CW + ch0), w1b = *(const f32x4*)(P.conv_w + CW + ch0 + 4);
;     const f32x4 w2a = *(const f32x4*)(P.conv_w + 2 * CW + ch0), w2b = *(const f32x4*)(P.conv_w + 2 * CW + ch0 + 4);
; __global__ void __launch_bounds__(NWAVES * 64, 2) mega_fwd(Args args) {
;     ...
;         if (gv) { const int j_ = (int)F.MISC[10] & 7, gw_ = ((int)F.MISC[10] >> 3) * NWAVES + F.wave;
;                   conv_fixup(F, P, 8 * (16 * (int)bar.x + j_), 8, gw_, 4 * NWAVES); conv_fixup(F, P, 8 * (16 * (int)bar.x + 15 - j_), 8, gw_, 4 * NWAVES); }
.LBB0_331:
	s_andn2_b64 vcc, exec, s[22:23]
	s_cbranch_vccnz .LBB0_337
	s_add_i32 s2, 0, 0x27d68
	v_mov_b32_e32 v1, s2
	ds_read_b32 v2, v1
	ds_read_b32 v1, v1
	s_waitcnt lgkmcnt(0)
	v_readfirstlane_b32 s22, v2
	v_readfirstlane_b32 s2, v1
	s_and_b32 s24, s2, -8
	s_add_i32 s2, s24, s85
	s_cmp_gt_i32 s2, 15
	s_cbranch_scc1 .LBB0_337
	s_and_b32 s55, s22, 7
	s_add_u32 s22, s14, 0xd400000
	s_addc_u32 s23, s15, 0
	v_mov_b32_e32 v27, 0
	v_lshlrev_b32_e32 v26, 4, v162
	v_lshl_add_u64 v[28:29], s[22:23], 0, v[26:27]
	v_lshl_add_u64 v[30:31], s[14:15], 0, v[26:27]
	v_lshlrev_b32_e32 v26, 5, v162
	v_lshl_add_u64 v[32:33], s[44:45], 0, v[26:27]
	s_movk_i32 s2, 0x1000
	global_load_dwordx4 v[2:5], v26, s[44:45]
	global_load_dwordx4 v[6:9], v26, s[44:45] offset:2048
	global_load_dwordx4 v[10:13], v26, s[44:45] offset:2064
	global_load_dwordx4 v[14:17], v26, s[44:45] offset:16
	v_add_co_u32_e32 v18, vcc, s2, v32
	s_mov_b64 s[44:45], 0x1000
	s_nop 0
	v_addc_co_u32_e32 v19, vcc, 0, v33, vcc
	v_lshl_add_u64 v[34:35], v[32:33], 0, s[44:45]
	global_load_dwordx4 v[18:21], v[18:19], off
	s_mov_b64 s[44:45], 0xf500000
	global_load_dwordx4 v[22:25], v[34:35], off offset:16
	s_lshl_b32 s2, s93, 7
	v_lshl_add_u64 v[30:31], v[30:31], 0, s[44:45]
	s_add_i32 s45, s85, s2
	s_lshl_b32 s44, s55, 3
	s_add_i32 s45, s45, s24
	s_or_b32 s25, s44, s2
	s_add_i32 s2, s45, s44
	v_lshlrev_b32_e32 v36, 3, v162
	s_movk_i32 s56, 0x3000
	s_movk_i32 s57, 0x4000
	s_mov_b32 s58, 0xffff0000
	s_bfe_u32 s33, s84, 0x10006
	s_sub_i32 s59, s25, 24
	s_sub_i32 s60, s2, 32
	s_lshl_b32 s61, s2, 5
	s_movk_i32 s62, 0x7fff
	s_cmp_lg_u32 s24, 0
	s_cbranch_scc1 .Lcf_wg1
	s_waitcnt vmcnt(0)
	v_mov_b32_e32 v38, v3
	v_mov_b32_e32 v39, v5
	v_mov_b32_e32 v40, v7
	v_mov_b32_e32 v41, v9
	v_mov_b32_e32 v3, v4
	v_mov_b32_e32 v7, v8
	v_mov_b32_e32 v4, v15
	v_mov_b32_e32 v5, v17
	v_mov_b32_e32 v8, v11
	v_mov_b32_e32 v9, v13
	v_mov_b32_e32 v15, v16
	v_mov_b32_e32 v11, v12
	v_mov_b32_e32 v12, v19
	v_mov_b32_e32 v13, v21
	v_mov_b32_e32 v19, v20
	v_mov_b32_e32 v16, v23
	v_mov_b32_e32 v17, v25
	v_mov_b32_e32 v23, v24
; #define GAS __attribute__((address_space(1)))
; #define CONV2(W, k0_, wa, wb, wc) { const float ylo = wa[k0_] * bflo_(um2.W) + wb[k0_] * bflo_(um1.W) + wc[k0_] * bflo_(u0.W); \
;                                     const float yhi = wa[k0_ + 1] * bfhi_(um2.W) + wb[k0_ + 1] * bfhi_(um1.W) + wc[k0_ + 1] * bfhi_(u0.W); \
;                                     o.W = pk2(bflo_(gb.W) * ylo, bfhi_(gb.W) * yhi); }
; __device__ __forceinline__ void conv_fixup(Frame& F, const Ptrs& P, int first, int count, int gw, int NGW) {
;     ...
;     for (int it = first + gw; it < first + count; it += NGW) {
;         const int m = (it >> 1) * 64 + (it & 1), b = m / SEQ, s = m % SEQ; const size_t ur = (size_t)b * LTOK + s + NMETA;
;         const v4u um2 = *(const GAS v4u*)(U + (ur - 2) * CW + ch0), um1 = *(const GAS v4u*)(U + (ur - 1) * CW + ch0), u0 = *(const GAS v4u*)(U + ur * CW + ch0), gb = *(const GAS v4u*)(GB + (size_t)m * CW + ch0);
;         v4u o;
;     ...
;         CONV2(x, 0, w0a, w1a, w2a) CONV2(y, 2, w0a, w1a, w2a) CONV2(z, 0, w0b, w1b, w2b) CONV2(w, 2, w0b, w1b, w2b)
;     ...
;         *(GAS v4u*)(BR + (size_t)m * 1024 + 512 + ch0) = o;
;     }
; __global__ void __launch_bounds__(NWAVES * 64, 2) mega_fwd(Args args) {
;     ...
;         if (gv) { const int j_ = (int)F.MISC[10] & 7, gw_ = ((int)F.MISC[10] >> 3) * NWAVES + F.wave;
;                   conv_fixup(F, P, 8 * (16 * (int)bar.x + j_), 8, gw_, 4 * NWAVES); conv_fixup(F, P, 8 * (16 * (int)bar.x + 15 - j_), 8, gw_, 4 * NWAVES); }
.LBB0_334:
	s_and_b32 s2, s61, 0xffffffc0
	s_or_b32 s24, s2, s33
	s_ashr_i32 s25, s24, 31
	s_lshr_b32 s2, s25, 20
	s_add_i32 s2, s24, s2
	s_ashr_i32 s63, s2, 12
	s_and_b32 s2, s2, 0xfffff000
	s_sub_i32 s2, s24, s2
	s_mul_hi_i32 s65, s63, 0x1010
	s_mulk_i32 s63, 0x1010
	s_ashr_i32 s66, s2, 31
	s_add_u32 s64, s63, s2
	s_addc_u32 s65, s65, s66
	s_lshl_b64 s[64:65], s[64:65], 10
	v_lshl_add_u64 v[20:21], v[28:29], 0, s[64:65]
	s_add_u32 s64, s22, s64
	v_add_co_u32_e32 v20, vcc, s56, v20
	v_lshlrev_b32_e32 v26, 1, v36
	s_nop 0
	v_addc_co_u32_e32 v21, vcc, 0, v21, vcc
	s_addc_u32 s65, s23, s65
	global_load_dwordx4 v[42:45], v[20:21], off offset:2048
	v_lshl_add_u64 v[20:21], s[64:65], 0, v[26:27]
	v_add_co_u32_e32 v46, vcc, s56, v20
	s_lshl_b64 s[66:67], s[24:25], 10
	s_nop 0
	v_addc_co_u32_e32 v47, vcc, 0, v21, vcc
	v_add_co_u32_e32 v20, vcc, s57, v20
	v_lshl_add_u64 v[24:25], v[30:31], 0, s[66:67]
	s_nop 0
	v_addc_co_u32_e32 v21, vcc, 0, v21, vcc
	global_load_dwordx4 v[46:49], v[46:47], off offset:3072
	s_nop 0
	global_load_dwordx4 v[50:53], v[20:21], off
	global_load_dwordx4 v[54:57], v[24:25], off
	s_lshl_b64 s[24:25], s[24:25], 11
	s_add_u32 s24, s14, s24
	s_addc_u32 s25, s15, s25
	v_lshl_add_u64 v[20:21], s[24:25], 0, v[26:27]
	s_add_i32 s60, s60, 32
	s_addk_i32 s61, 0x400
	v_add_co_u32_e32 v20, vcc, 0x19500000, v20
	s_cmp_lt_i32 s60, s59
	s_nop 0
	v_addc_co_u32_e32 v21, vcc, 0, v21, vcc
	s_waitcnt vmcnt(3)
	v_lshlrev_b32_e32 v25, 16, v43
	v_lshlrev_b32_e32 v24, 16, v42
	v_and_b32_e32 v43, 0xffff0000, v43
	v_and_b32_e32 v42, 0xffff0000, v42
	v_lshlrev_b32_e32 v59, 16, v45
	v_lshlrev_b32_e32 v58, 16, v44
	v_and_b32_e32 v45, 0xffff0000, v45
	v_and_b32_e32 v44, 0xffff0000, v44
	s_waitcnt vmcnt(2)
	v_lshlrev_b32_e32 v61, 16, v47
	v_lshlrev_b32_e32 v60, 16, v46
	v_and_b32_e32 v47, 0xffff0000, v47
	v_and_b32_e32 v46, 0xffff0000, v46
	v_lshlrev_b32_e32 v67, 16, v49
	v_lshlrev_b32_e32 v66, 16, v48
	v_and_b32_e32 v49, 0xffff0000, v49
	v_and_b32_e32 v48, 0xffff0000, v48
	v_pk_mul_f32 v[60:61], v[6:7], v[60:61]
	v_pk_mul_f32 v[46:47], v[40:41], v[46:47]
	v_pk_mul_f32 v[66:67], v[10:11], v[66:67]
	v_pk_mul_f32 v[48:49], v[8:9], v[48:49]
	s_waitcnt vmcnt(1)
	v_lshlrev_b32_e32 v63, 16, v51
	v_lshlrev_b32_e32 v62, 16, v50
	v_lshlrev_b32_e32 v69, 16, v53
	v_lshlrev_b32_e32 v68, 16, v52
	v_and_b32_e32 v53, 0xffff0000, v53
	v_and_b32_e32 v52, 0xffff0000, v52
	v_pk_fma_f32 v[24:25], v[2:3], v[24:25], v[60:61]
	v_pk_fma_f32 v[42:43], v[38:39], v[42:43], v[46:47]
	v_pk_fma_f32 v[46:47], v[14:15], v[58:59], v[66:67]
	v_pk_fma_f32 v[44:45], v[4:5], v[44:45], v[48:49]
	v_and_b32_e32 v51, 0xffff0000, v51
	v_and_b32_e32 v50, 0xffff0000, v50
	s_waitcnt vmcnt(0)
	v_lshlrev_b32_e32 v65, 16, v55
	v_lshlrev_b32_e32 v64, 16, v54
	v_lshlrev_b32_e32 v71, 16, v57
	v_lshlrev_b32_e32 v70, 16, v56
	v_and_b32_e32 v57, 0xffff0000, v57
	v_and_b32_e32 v56, 0xffff0000, v56
	v_pk_fma_f32 v[24:25], v[18:19], v[62:63], v[24:25]
	v_pk_fma_f32 v[46:47], v[22:23], v[68:69], v[46:47]
	v_pk_fma_f32 v[44:45], v[16:17], v[52:53], v[44:45]
	v_and_b32_e32 v55, 0xffff0000, v55
	v_and_b32_e32 v54, 0xffff0000, v54
	v_pk_fma_f32 v[42:43], v[12:13], v[50:51], v[42:43]
	v_pk_mul_f32 v[24:25], v[24:25], v[64:65]
	v_pk_mul_f32 v[46:47], v[46:47], v[70:71]
	v_pk_mul_f32 v[44:45], v[44:45], v[56:57]
	v_pk_mul_f32 v[42:43], v[42:43], v[54:55]
	v_bfe_u32 v1, v45, 16, 1
	v_bfe_u32 v37, v44, 16, 1
	v_bfe_u32 v50, v24, 16, 1
	v_bfe_u32 v51, v25, 16, 1
	v_bfe_u32 v52, v46, 16, 1
	v_bfe_u32 v53, v47, 16, 1
	v_bfe_u32 v48, v43, 16, 1
	v_bfe_u32 v49, v42, 16, 1
	v_add3_u32 v37, v44, v37, s62
	v_add3_u32 v1, v45, v1, s62
	v_add3_u32 v44, v47, v53, s62
	v_add3_u32 v45, v46, v52, s62
	v_add3_u32 v25, v25, v51, s62
	v_add3_u32 v24, v24, v50, s62
	v_add3_u32 v42, v42, v49, s62
	v_add3_u32 v43, v43, v48, s62
	v_lshrrev_b32_e32 v24, 16, v24
	v_lshrrev_b32_e32 v25, 16, v25
	v_lshrrev_b32_e32 v46, 16, v45
	v_lshrrev_b32_e32 v44, 16, v44
	v_and_or_b32 v45, v1, s58, v44
	v_and_or_b32 v44, v37, s58, v46
	v_and_or_b32 v43, v43, s58, v25
	v_and_or_b32 v42, v42, s58, v24
	global_store_dwordx4 v[20:21], v[42:45], off offset:1024
	s_cbranch_scc1 .LBB0_334
	s_branch .LBB0_337
.Lcf_wg1:
	v_lshlrev_b32_e32 v26, 1, v36
	s_sub_i32 s45, s45, 8
.Lcf_call2:
	global_load_dwordx4 v[2:5], v[32:33], off
	global_load_dwordx4 v[6:9], v[32:33], off offset:2048
	global_load_dwordx4 v[10:13], v[34:35], off
	global_load_dwordx4 v[14:17], v[32:33], off offset:16
	global_load_dwordx4 v[18:21], v[32:33], off offset:2064
	global_load_dwordx4 v[22:25], v[34:35], off offset:16
	s_lshl_b32 s2, s93, 4
	s_or_b32 s2, s2, 15
	s_sub_i32 s24, s45, s44
	s_sub_i32 s2, s2, s55
	s_add_i32 s57, s24, 0x58
	s_lshl_b32 s24, s24, 5
	s_lshl_b32 s2, s2, 3
	s_movk_i32 s44, 0x3000
	v_mov_b32_e32 v27, 0
	s_movk_i32 s45, 0x4000
	s_mov_b32 s56, 0xffff0000
	s_add_i32 s55, s24, 0xf00
	s_sub_i32 s58, s2, 24
	s_movk_i32 s59, 0x7fff
	s_waitcnt vmcnt(5)
	v_mov_b32_e32 v32, v3
	v_mov_b32_e32 v33, v5
	s_waitcnt vmcnt(4)
	v_mov_b32_e32 v34, v7
	v_mov_b32_e32 v35, v9
	s_waitcnt vmcnt(3)
	v_mov_b32_e32 v36, v11
	v_mov_b32_e32 v37, v13
	v_mov_b32_e32 v3, v4
	v_mov_b32_e32 v7, v8
	v_mov_b32_e32 v11, v12
	s_waitcnt vmcnt(2)
	v_mov_b32_e32 v4, v15
	v_mov_b32_e32 v5, v17
	s_waitcnt vmcnt(1)
	v_mov_b32_e32 v8, v19
	v_mov_b32_e32 v9, v21
	s_waitcnt vmcnt(0)
	v_mov_b32_e32 v12, v23
	v_mov_b32_e32 v13, v25
	v_mov_b32_e32 v15, v16
	v_mov_b32_e32 v19, v20
	v_mov_b32_e32 v23, v24
